# local barriers at 9 seams; seams 1,6,8 additionally wait on the neighbour groups whose ACT rows the next phase overlays (WAR fence), everything else as before
# speedup vs baseline: 1.0091x; 1.0091x over previous
.LBB0_515:
	s_waitcnt vmcnt(0)
	s_waitcnt vmcnt(0) lgkmcnt(0)
	s_barrier
	s_and_saveexec_b64 s[0:1], s[62:63]
	s_cbranch_execz .LBB0_202
	v_readlane_b32 s6, v254, 49
	s_mov_b32 s9, 0x19f3
	s_nop 0
	s_lshr_b32 s12, s9, s6
	s_and_b32 s12, s12, s100
	s_and_b32 s12, s12, 1
	s_cmp_eq_u32 s12, 0
	s_cbranch_scc1 .Lgbar
	s_lshl_b32 s12, 2, s6
	s_sub_i32 s12, s12, 1
	s_and_b32 s12, s12, s9
	s_bcnt1_i32_b32 s12, s12
	s_lshl_b32 s9, s12, 5
	v_readlane_b32 s8, v252, 0
	v_readlane_b32 s10, v252, 45
	v_readlane_b32 s11, v252, 46
	s_and_b32 s8, s8, 7
	s_mov_b32 s16, 0x0e060301
	s_mov_b32 s17, 0xb058281c
	s_cmp_eq_u32 s6, 1
	s_cbranch_scc1 .Llb_tab
	s_mov_b32 s16, 0x0a060301
	s_mov_b32 s17, 0x88482414
	s_cmp_eq_u32 s6, 6
	s_cbranch_scc1 .Llb_tab
	s_mov_b32 s16, 0x0c060301
	s_mov_b32 s17, 0xa070381c
	s_cmp_eq_u32 s6, 8
	s_cbranch_scc1 .Llb_tab
	s_lshl_b32 s13, 1, s8
	s_branch .Llb_have
.Llb_tab:
	s_lshl_b32 s14, s8, 3
	s_lshr_b64 s[16:17], s[16:17], s14
	s_and_b32 s13, s16, 0xff
.Llb_have:
	s_lshl_b32 s8, s8, 6
	s_add_u32 s10, s10, 0xe3600
	s_addc_u32 s11, s11, 0
	v_mov_b32_e32 v1, 1
	v_mov_b32_e32 v2, s8
	s_nop 0
	global_atomic_add v2, v1, s[10:11]
	s_mov_b64 exec, 0xff
	v_mbcnt_lo_u32_b32 v2, -1, 0
	v_lshlrev_b32_e32 v2, 6, v2
	s_mov_b32 s12, 0
